# speedup vs baseline: 1.0228x; 1.0228x over previous
; __device__ __forceinline__ unsigned cvt_pk(float lo, float hi) { unsigned r; asm("v_cvt_pk_bf16_f32 %0, %1, %2" : "=v"(r) : "v"(lo), "v"(hi)); return r; }
; __device__ __forceinline__ float bflo(unsigned w) { return __uint_as_float(w << 16); }
; __device__ __forceinline__ float bfhi(unsigned w) { return __uint_as_float(w & 0xffff0000u); }
;     __device__ __forceinline__ void operator()(const f32x4 (&acc)[2][2][4][2], const Unit& u, int wr, int wc, int fr, int fq, LAS unsigned char*) const {
;     ...
; #pragma unroll
;         for (int ai = 0; ai < 2; ++ai)
; #pragma unroll
;             for (int m = 0; m < 4; ++m) { bf16_t* rowp = X + (size_t)(u.pm * 256 + ai * 128 + m * 16 + r0) * D + colt;
; #pragma unroll
;                 for (int bj = 0; bj < 2; ++bj) { const u32x4 xr = *(const u32x4*)(rowp + bj * 128); const f32x4 v0 = acc[ai][bj][m][0], v1 = acc[ai][bj][m][1];
;                     u32x4 w; w.x = cvt_pk(bflo(xr.x) * ALPHA + v0[0], bfhi(xr.x) * ALPHA + v0[1]); w.y = cvt_pk(bflo(xr.y) * ALPHA + v0[2], bfhi(xr.y) * ALPHA + v0[3]);
;                     w.z = cvt_pk(bflo(xr.z) * ALPHA + v1[0], bfhi(xr.z) * ALPHA + v1[1]); w.w = cvt_pk(bflo(xr.w) * ALPHA + v1[2], bfhi(xr.w) * ALPHA + v1[3]);
;                     if (!dry) *(u32x4*)(rowp + bj * 128) = w; } }
.LBB0_1680:
	v_lshl_or_b32 v178, s60, 8, v141
	s_mov_b64 s[60:61], -1
	s_cmp_gt_i32 s20, -1
	v_ashrrev_i32_e32 v179, 31, v178
	s_cbranch_scc1 .LBB0_1682
	s_lshl_b32 s5, s58, 8
	v_add_u32_e32 v130, s5, v140
	v_ashrrev_i32_e32 v131, 31, v130
	v_lshlrev_b64 v[130:131], 12, v[130:131]
	v_lshl_add_u64 v[228:229], s[24:25], 0, v[130:131]
	v_lshlrev_b64 v[130:131], 1, v[178:179]
	v_lshl_add_u64 v[228:229], v[228:229], 0, v[130:131]
	global_load_dwordx4 v[188:191], v[228:229], off
	s_mov_b64 s[60:61], 0
	global_load_dwordx4 v[192:195], v[228:229], off offset:256
	v_add_u32_e32 v230, s5, v142
	v_ashrrev_i32_e32 v231, 31, v230
	v_lshlrev_b64 v[230:231], 12, v[230:231]
	v_lshl_add_u64 v[230:231], s[24:25], 0, v[230:231]
	v_lshl_add_u64 v[230:231], v[230:231], 0, v[130:131]
	global_load_dwordx4 v[196:199], v[230:231], off
	global_load_dwordx4 v[200:203], v[230:231], off offset:256
	v_add_u32_e32 v232, s5, v144
	v_ashrrev_i32_e32 v233, 31, v232
	v_lshlrev_b64 v[232:233], 12, v[232:233]
	v_lshl_add_u64 v[232:233], s[24:25], 0, v[232:233]
	v_lshl_add_u64 v[232:233], v[232:233], 0, v[130:131]
	global_load_dwordx4 v[204:207], v[232:233], off
	global_load_dwordx4 v[216:219], v[232:233], off offset:256
	v_add_u32_e32 v234, s5, v146
	v_ashrrev_i32_e32 v235, 31, v234
	v_lshlrev_b64 v[234:235], 12, v[234:235]
	v_lshl_add_u64 v[234:235], s[24:25], 0, v[234:235]
	v_lshl_add_u64 v[234:235], v[234:235], 0, v[130:131]
	global_load_dwordx4 v[220:223], v[234:235], off
	global_load_dwordx4 v[224:227], v[234:235], off offset:256
	s_waitcnt vmcnt(0)
	v_lshlrev_b32_e32 v145, 16, v188
	v_and_b32_e32 v147, 0xffff0000, v188
	v_fmamk_f32 v145, v145, 0x3fb504f3, v126
	v_fmamk_f32 v147, v147, 0x3fb504f3, v127
	v_cvt_pk_bf16_f32 v188, v145, v147
	v_lshlrev_b32_e32 v145, 16, v189
	v_and_b32_e32 v147, 0xffff0000, v189
	v_fmamk_f32 v145, v145, 0x3fb504f3, v128
	v_fmamk_f32 v147, v147, 0x3fb504f3, v129
	v_cvt_pk_bf16_f32 v189, v145, v147
	v_lshlrev_b32_e32 v145, 16, v190
	v_and_b32_e32 v147, 0xffff0000, v190
	v_fmamk_f32 v145, v145, 0x3fb504f3, v122
	v_fmamk_f32 v147, v147, 0x3fb504f3, v123
	v_cvt_pk_bf16_f32 v190, v145, v147
	v_lshlrev_b32_e32 v145, 16, v191
	v_and_b32_e32 v147, 0xffff0000, v191
	v_fmamk_f32 v145, v145, 0x3fb504f3, v124
	v_fmamk_f32 v147, v147, 0x3fb504f3, v125
	v_cvt_pk_bf16_f32 v191, v145, v147
	global_store_dwordx4 v[228:229], v[188:191], off
	v_lshlrev_b32_e32 v145, 16, v192
	v_and_b32_e32 v147, 0xffff0000, v192
	v_fmamk_f32 v145, v145, 0x3fb504f3, v118
	v_fmamk_f32 v147, v147, 0x3fb504f3, v119
	v_cvt_pk_bf16_f32 v192, v145, v147
	v_lshlrev_b32_e32 v145, 16, v193
	v_and_b32_e32 v147, 0xffff0000, v193
	v_fmamk_f32 v145, v145, 0x3fb504f3, v120
	v_fmamk_f32 v147, v147, 0x3fb504f3, v121
	v_cvt_pk_bf16_f32 v193, v145, v147
	v_lshlrev_b32_e32 v145, 16, v194
	v_and_b32_e32 v147, 0xffff0000, v194
	v_fmamk_f32 v145, v145, 0x3fb504f3, v114
	v_fmamk_f32 v147, v147, 0x3fb504f3, v115
	v_cvt_pk_bf16_f32 v194, v145, v147
	v_lshlrev_b32_e32 v145, 16, v195
	v_and_b32_e32 v147, 0xffff0000, v195
	v_fmamk_f32 v145, v145, 0x3fb504f3, v116
	v_fmamk_f32 v147, v147, 0x3fb504f3, v117
	v_cvt_pk_bf16_f32 v195, v145, v147
	global_store_dwordx4 v[228:229], v[192:195], off offset:256
	v_lshlrev_b32_e32 v145, 16, v196
	v_and_b32_e32 v147, 0xffff0000, v196
	v_fmamk_f32 v145, v145, 0x3fb504f3, v110
	v_fmamk_f32 v147, v147, 0x3fb504f3, v111
	v_cvt_pk_bf16_f32 v196, v145, v147
	v_lshlrev_b32_e32 v145, 16, v197
	v_and_b32_e32 v147, 0xffff0000, v197
	v_fmamk_f32 v145, v145, 0x3fb504f3, v112
	v_fmamk_f32 v147, v147, 0x3fb504f3, v113
	v_cvt_pk_bf16_f32 v197, v145, v147
	v_lshlrev_b32_e32 v145, 16, v198
	v_and_b32_e32 v147, 0xffff0000, v198
	v_fmamk_f32 v145, v145, 0x3fb504f3, v106
	v_fmamk_f32 v147, v147, 0x3fb504f3, v107
	v_cvt_pk_bf16_f32 v198, v145, v147
	v_lshlrev_b32_e32 v145, 16, v199
	v_and_b32_e32 v147, 0xffff0000, v199
	v_fmamk_f32 v145, v145, 0x3fb504f3, v108
	v_fmamk_f32 v147, v147, 0x3fb504f3, v109
	v_cvt_pk_bf16_f32 v199, v145, v147
	global_store_dwordx4 v[230:231], v[196:199], off
	v_lshlrev_b32_e32 v145, 16, v200
	v_and_b32_e32 v147, 0xffff0000, v200
	v_fmamk_f32 v145, v145, 0x3fb504f3, v102
	v_fmamk_f32 v147, v147, 0x3fb504f3, v103
	v_cvt_pk_bf16_f32 v200, v145, v147
	v_lshlrev_b32_e32 v145, 16, v201
	v_and_b32_e32 v147, 0xffff0000, v201
	v_fmamk_f32 v145, v145, 0x3fb504f3, v104
	v_fmamk_f32 v147, v147, 0x3fb504f3, v105
	v_cvt_pk_bf16_f32 v201, v145, v147
	v_lshlrev_b32_e32 v145, 16, v202
	v_and_b32_e32 v147, 0xffff0000, v202
	v_fmamk_f32 v145, v145, 0x3fb504f3, v98
	v_fmamk_f32 v147, v147, 0x3fb504f3, v99
	v_cvt_pk_bf16_f32 v202, v145, v147
	v_lshlrev_b32_e32 v145, 16, v203
	v_and_b32_e32 v147, 0xffff0000, v203
	v_fmamk_f32 v145, v145, 0x3fb504f3, v100
	v_fmamk_f32 v147, v147, 0x3fb504f3, v101
	v_cvt_pk_bf16_f32 v203, v145, v147
	global_store_dwordx4 v[230:231], v[200:203], off offset:256
	v_lshlrev_b32_e32 v145, 16, v204
	v_and_b32_e32 v147, 0xffff0000, v204
	v_fmamk_f32 v145, v145, 0x3fb504f3, v94
	v_fmamk_f32 v147, v147, 0x3fb504f3, v95
	v_cvt_pk_bf16_f32 v204, v145, v147
	v_lshlrev_b32_e32 v145, 16, v205
	v_and_b32_e32 v147, 0xffff0000, v205
	v_fmamk_f32 v145, v145, 0x3fb504f3, v96
	v_fmamk_f32 v147, v147, 0x3fb504f3, v97
	v_cvt_pk_bf16_f32 v205, v145, v147
	v_lshlrev_b32_e32 v145, 16, v206
	v_and_b32_e32 v147, 0xffff0000, v206
	v_fmamk_f32 v145, v145, 0x3fb504f3, v90
	v_fmamk_f32 v147, v147, 0x3fb504f3, v91
	v_cvt_pk_bf16_f32 v206, v145, v147
	v_lshlrev_b32_e32 v145, 16, v207
	v_and_b32_e32 v147, 0xffff0000, v207
	v_fmamk_f32 v145, v145, 0x3fb504f3, v92
	v_fmamk_f32 v147, v147, 0x3fb504f3, v93
	v_cvt_pk_bf16_f32 v207, v145, v147
	global_store_dwordx4 v[232:233], v[204:207], off
; __device__ __forceinline__ unsigned cvt_pk(float lo, float hi) { unsigned r; asm("v_cvt_pk_bf16_f32 %0, %1, %2" : "=v"(r) : "v"(lo), "v"(hi)); return r; }
; __device__ __forceinline__ float bflo(unsigned w) { return __uint_as_float(w << 16); }
; __device__ __forceinline__ float bfhi(unsigned w) { return __uint_as_float(w & 0xffff0000u); }
;     __device__ __forceinline__ void operator()(const f32x4 (&acc)[2][2][4][2], const Unit& u, int wr, int wc, int fr, int fq, LAS unsigned char*) const {
;     ...
; #pragma unroll
;         for (int ai = 0; ai < 2; ++ai)
; #pragma unroll
;             for (int m = 0; m < 4; ++m) { bf16_t* rowp = X + (size_t)(u.pm * 256 + ai * 128 + m * 16 + r0) * D + colt;
; #pragma unroll
;                 for (int bj = 0; bj < 2; ++bj) { const u32x4 xr = *(const u32x4*)(rowp + bj * 128); const f32x4 v0 = acc[ai][bj][m][0], v1 = acc[ai][bj][m][1];
;                     u32x4 w; w.x = cvt_pk(bflo(xr.x) * ALPHA + v0[0], bfhi(xr.x) * ALPHA + v0[1]); w.y = cvt_pk(bflo(xr.y) * ALPHA + v0[2], bfhi(xr.y) * ALPHA + v0[3]);
;                     w.z = cvt_pk(bflo(xr.z) * ALPHA + v1[0], bfhi(xr.z) * ALPHA + v1[1]); w.w = cvt_pk(bflo(xr.w) * ALPHA + v1[2], bfhi(xr.w) * ALPHA + v1[3]);
;                     if (!dry) *(u32x4*)(rowp + bj * 128) = w; } }
	v_lshlrev_b32_e32 v145, 16, v216
	v_and_b32_e32 v147, 0xffff0000, v216
	v_fmamk_f32 v145, v145, 0x3fb504f3, v86
	v_fmamk_f32 v147, v147, 0x3fb504f3, v87
	v_cvt_pk_bf16_f32 v216, v145, v147
	v_lshlrev_b32_e32 v145, 16, v217
	v_and_b32_e32 v147, 0xffff0000, v217
	v_fmamk_f32 v145, v145, 0x3fb504f3, v88
	v_fmamk_f32 v147, v147, 0x3fb504f3, v89
	v_cvt_pk_bf16_f32 v217, v145, v147
	v_lshlrev_b32_e32 v145, 16, v218
	v_and_b32_e32 v147, 0xffff0000, v218
	v_fmamk_f32 v145, v145, 0x3fb504f3, v82
	v_fmamk_f32 v147, v147, 0x3fb504f3, v83
	v_cvt_pk_bf16_f32 v218, v145, v147
	v_lshlrev_b32_e32 v145, 16, v219
	v_and_b32_e32 v147, 0xffff0000, v219
	v_fmamk_f32 v145, v145, 0x3fb504f3, v84
	v_fmamk_f32 v147, v147, 0x3fb504f3, v85
	v_cvt_pk_bf16_f32 v219, v145, v147
	global_store_dwordx4 v[232:233], v[216:219], off offset:256
	v_lshlrev_b32_e32 v145, 16, v220
	v_and_b32_e32 v147, 0xffff0000, v220
	v_fmamk_f32 v145, v145, 0x3fb504f3, v78
	v_fmamk_f32 v147, v147, 0x3fb504f3, v79
	v_cvt_pk_bf16_f32 v220, v145, v147
	v_lshlrev_b32_e32 v145, 16, v221
	v_and_b32_e32 v147, 0xffff0000, v221
	v_fmamk_f32 v145, v145, 0x3fb504f3, v80
	v_fmamk_f32 v147, v147, 0x3fb504f3, v81
	v_cvt_pk_bf16_f32 v221, v145, v147
	v_lshlrev_b32_e32 v145, 16, v222
	v_and_b32_e32 v147, 0xffff0000, v222
	v_fmamk_f32 v145, v145, 0x3fb504f3, v74
	v_fmamk_f32 v147, v147, 0x3fb504f3, v75
	v_cvt_pk_bf16_f32 v222, v145, v147
	v_lshlrev_b32_e32 v145, 16, v223
	v_and_b32_e32 v147, 0xffff0000, v223
	v_fmamk_f32 v145, v145, 0x3fb504f3, v76
	v_fmamk_f32 v147, v147, 0x3fb504f3, v77
	v_cvt_pk_bf16_f32 v223, v145, v147
	global_store_dwordx4 v[234:235], v[220:223], off
	v_lshlrev_b32_e32 v145, 16, v224
	v_and_b32_e32 v147, 0xffff0000, v224
	v_fmamk_f32 v145, v145, 0x3fb504f3, v70
	v_fmamk_f32 v147, v147, 0x3fb504f3, v71
	v_cvt_pk_bf16_f32 v224, v145, v147
	v_lshlrev_b32_e32 v145, 16, v225
	v_and_b32_e32 v147, 0xffff0000, v225
	v_fmamk_f32 v145, v145, 0x3fb504f3, v72
	v_fmamk_f32 v147, v147, 0x3fb504f3, v73
	v_cvt_pk_bf16_f32 v225, v145, v147
	v_lshlrev_b32_e32 v145, 16, v226
	v_and_b32_e32 v147, 0xffff0000, v226
	v_fmamk_f32 v145, v145, 0x3fb504f3, v66
	v_fmamk_f32 v147, v147, 0x3fb504f3, v67
	v_cvt_pk_bf16_f32 v226, v145, v147
	v_lshlrev_b32_e32 v145, 16, v227
	v_and_b32_e32 v147, 0xffff0000, v227
	v_fmamk_f32 v145, v145, 0x3fb504f3, v68
	v_fmamk_f32 v147, v147, 0x3fb504f3, v69
	v_cvt_pk_bf16_f32 v227, v145, v147
	global_store_dwordx4 v[234:235], v[224:227], off offset:256
	v_add_u32_e32 v228, s5, v148
	v_ashrrev_i32_e32 v229, 31, v228
	v_lshlrev_b64 v[228:229], 12, v[228:229]
	v_lshl_add_u64 v[228:229], s[24:25], 0, v[228:229]
	v_lshl_add_u64 v[228:229], v[228:229], 0, v[130:131]
	global_load_dwordx4 v[188:191], v[228:229], off
	global_load_dwordx4 v[192:195], v[228:229], off offset:256
	v_add_u32_e32 v230, s5, v150
	v_ashrrev_i32_e32 v231, 31, v230
	v_lshlrev_b64 v[230:231], 12, v[230:231]
	v_lshl_add_u64 v[230:231], s[24:25], 0, v[230:231]
	v_lshl_add_u64 v[230:231], v[230:231], 0, v[130:131]
	global_load_dwordx4 v[196:199], v[230:231], off
	global_load_dwordx4 v[200:203], v[230:231], off offset:256
	v_add_u32_e32 v232, s5, v152
	v_ashrrev_i32_e32 v233, 31, v232
	v_lshlrev_b64 v[232:233], 12, v[232:233]
	v_lshl_add_u64 v[232:233], s[24:25], 0, v[232:233]
	v_lshl_add_u64 v[232:233], v[232:233], 0, v[130:131]
	global_load_dwordx4 v[204:207], v[232:233], off
	global_load_dwordx4 v[216:219], v[232:233], off offset:256
	v_add_u32_e32 v132, s5, v154
	v_ashrrev_i32_e32 v133, 31, v132
	v_lshlrev_b64 v[132:133], 12, v[132:133]
	v_lshl_add_u64 v[132:133], s[24:25], 0, v[132:133]
	v_lshl_add_u64 v[234:235], v[132:133], 0, v[130:131]
	global_load_dwordx4 v[220:223], v[234:235], off
	global_load_dwordx4 v[224:227], v[234:235], off offset:256
	s_waitcnt vmcnt(0)
; __device__ __forceinline__ unsigned cvt_pk(float lo, float hi) { unsigned r; asm("v_cvt_pk_bf16_f32 %0, %1, %2" : "=v"(r) : "v"(lo), "v"(hi)); return r; }
; __device__ __forceinline__ float bflo(unsigned w) { return __uint_as_float(w << 16); }
; __device__ __forceinline__ float bfhi(unsigned w) { return __uint_as_float(w & 0xffff0000u); }
;     __device__ __forceinline__ void operator()(const f32x4 (&acc)[2][2][4][2], const Unit& u, int wr, int wc, int fr, int fq, LAS unsigned char*) const {
;     ...
; #pragma unroll
;         for (int ai = 0; ai < 2; ++ai)
; #pragma unroll
;             for (int m = 0; m < 4; ++m) { bf16_t* rowp = X + (size_t)(u.pm * 256 + ai * 128 + m * 16 + r0) * D + colt;
; #pragma unroll
;                 for (int bj = 0; bj < 2; ++bj) { const u32x4 xr = *(const u32x4*)(rowp + bj * 128); const f32x4 v0 = acc[ai][bj][m][0], v1 = acc[ai][bj][m][1];
;                     u32x4 w; w.x = cvt_pk(bflo(xr.x) * ALPHA + v0[0], bfhi(xr.x) * ALPHA + v0[1]); w.y = cvt_pk(bflo(xr.y) * ALPHA + v0[2], bfhi(xr.y) * ALPHA + v0[3]);
;                     w.z = cvt_pk(bflo(xr.z) * ALPHA + v1[0], bfhi(xr.z) * ALPHA + v1[1]); w.w = cvt_pk(bflo(xr.w) * ALPHA + v1[2], bfhi(xr.w) * ALPHA + v1[3]);
;                     if (!dry) *(u32x4*)(rowp + bj * 128) = w; } }
	v_lshlrev_b32_e32 v145, 16, v188
	v_and_b32_e32 v147, 0xffff0000, v188
	v_fmamk_f32 v145, v145, 0x3fb504f3, v62
	v_fmamk_f32 v147, v147, 0x3fb504f3, v63
	v_cvt_pk_bf16_f32 v188, v145, v147
	v_lshlrev_b32_e32 v145, 16, v189
	v_and_b32_e32 v147, 0xffff0000, v189
	v_fmamk_f32 v145, v145, 0x3fb504f3, v64
	v_fmamk_f32 v147, v147, 0x3fb504f3, v65
	v_cvt_pk_bf16_f32 v189, v145, v147
	v_lshlrev_b32_e32 v145, 16, v190
	v_and_b32_e32 v147, 0xffff0000, v190
	v_fmamk_f32 v145, v145, 0x3fb504f3, v58
	v_fmamk_f32 v147, v147, 0x3fb504f3, v59
	v_cvt_pk_bf16_f32 v190, v145, v147
	v_lshlrev_b32_e32 v145, 16, v191
	v_and_b32_e32 v147, 0xffff0000, v191
	v_fmamk_f32 v145, v145, 0x3fb504f3, v60
	v_fmamk_f32 v147, v147, 0x3fb504f3, v61
	v_cvt_pk_bf16_f32 v191, v145, v147
	global_store_dwordx4 v[228:229], v[188:191], off
	v_lshlrev_b32_e32 v145, 16, v192
	v_and_b32_e32 v147, 0xffff0000, v192
	v_fmamk_f32 v145, v145, 0x3fb504f3, v54
	v_fmamk_f32 v147, v147, 0x3fb504f3, v55
	v_cvt_pk_bf16_f32 v192, v145, v147
	v_lshlrev_b32_e32 v145, 16, v193
	v_and_b32_e32 v147, 0xffff0000, v193
	v_fmamk_f32 v145, v145, 0x3fb504f3, v56
	v_fmamk_f32 v147, v147, 0x3fb504f3, v57
	v_cvt_pk_bf16_f32 v193, v145, v147
	v_lshlrev_b32_e32 v145, 16, v194
	v_and_b32_e32 v147, 0xffff0000, v194
	v_fmamk_f32 v145, v145, 0x3fb504f3, v50
	v_fmamk_f32 v147, v147, 0x3fb504f3, v51
	v_cvt_pk_bf16_f32 v194, v145, v147
	v_lshlrev_b32_e32 v145, 16, v195
	v_and_b32_e32 v147, 0xffff0000, v195
	v_fmamk_f32 v145, v145, 0x3fb504f3, v52
	v_fmamk_f32 v147, v147, 0x3fb504f3, v53
	v_cvt_pk_bf16_f32 v195, v145, v147
	global_store_dwordx4 v[228:229], v[192:195], off offset:256
	v_lshlrev_b32_e32 v145, 16, v196
	v_and_b32_e32 v147, 0xffff0000, v196
	v_fmamk_f32 v145, v145, 0x3fb504f3, v46
	v_fmamk_f32 v147, v147, 0x3fb504f3, v47
	v_cvt_pk_bf16_f32 v196, v145, v147
	v_lshlrev_b32_e32 v145, 16, v197
	v_and_b32_e32 v147, 0xffff0000, v197
	v_fmamk_f32 v145, v145, 0x3fb504f3, v48
	v_fmamk_f32 v147, v147, 0x3fb504f3, v49
	v_cvt_pk_bf16_f32 v197, v145, v147
	v_lshlrev_b32_e32 v145, 16, v198
	v_and_b32_e32 v147, 0xffff0000, v198
	v_fmamk_f32 v145, v145, 0x3fb504f3, v42
	v_fmamk_f32 v147, v147, 0x3fb504f3, v43
	v_cvt_pk_bf16_f32 v198, v145, v147
	v_lshlrev_b32_e32 v145, 16, v199
	v_and_b32_e32 v147, 0xffff0000, v199
	v_fmamk_f32 v145, v145, 0x3fb504f3, v44
	v_fmamk_f32 v147, v147, 0x3fb504f3, v45
	v_cvt_pk_bf16_f32 v199, v145, v147
	global_store_dwordx4 v[230:231], v[196:199], off
	v_lshlrev_b32_e32 v145, 16, v200
	v_and_b32_e32 v147, 0xffff0000, v200
	v_fmamk_f32 v145, v145, 0x3fb504f3, v38
	v_fmamk_f32 v147, v147, 0x3fb504f3, v39
	v_cvt_pk_bf16_f32 v200, v145, v147
	v_lshlrev_b32_e32 v145, 16, v201
	v_and_b32_e32 v147, 0xffff0000, v201
	v_fmamk_f32 v145, v145, 0x3fb504f3, v40
	v_fmamk_f32 v147, v147, 0x3fb504f3, v41
	v_cvt_pk_bf16_f32 v201, v145, v147
	v_lshlrev_b32_e32 v145, 16, v202
	v_and_b32_e32 v147, 0xffff0000, v202
	v_fmamk_f32 v145, v145, 0x3fb504f3, v34
	v_fmamk_f32 v147, v147, 0x3fb504f3, v35
	v_cvt_pk_bf16_f32 v202, v145, v147
	v_lshlrev_b32_e32 v145, 16, v203
	v_and_b32_e32 v147, 0xffff0000, v203
	v_fmamk_f32 v145, v145, 0x3fb504f3, v36
	v_fmamk_f32 v147, v147, 0x3fb504f3, v37
	v_cvt_pk_bf16_f32 v203, v145, v147
	global_store_dwordx4 v[230:231], v[200:203], off offset:256
	v_lshlrev_b32_e32 v145, 16, v204
	v_and_b32_e32 v147, 0xffff0000, v204
	v_fmamk_f32 v145, v145, 0x3fb504f3, v30
	v_fmamk_f32 v147, v147, 0x3fb504f3, v31
	v_cvt_pk_bf16_f32 v204, v145, v147
	v_lshlrev_b32_e32 v145, 16, v205
	v_and_b32_e32 v147, 0xffff0000, v205
	v_fmamk_f32 v145, v145, 0x3fb504f3, v32
	v_fmamk_f32 v147, v147, 0x3fb504f3, v33
	v_cvt_pk_bf16_f32 v205, v145, v147
	v_lshlrev_b32_e32 v145, 16, v206
	v_and_b32_e32 v147, 0xffff0000, v206
	v_fmamk_f32 v145, v145, 0x3fb504f3, v26
	v_fmamk_f32 v147, v147, 0x3fb504f3, v27
	v_cvt_pk_bf16_f32 v206, v145, v147
	v_lshlrev_b32_e32 v145, 16, v207
	v_and_b32_e32 v147, 0xffff0000, v207
	v_fmamk_f32 v145, v145, 0x3fb504f3, v28
	v_fmamk_f32 v147, v147, 0x3fb504f3, v29
	v_cvt_pk_bf16_f32 v207, v145, v147
	global_store_dwordx4 v[232:233], v[204:207], off
	v_lshlrev_b32_e32 v145, 16, v216
	v_and_b32_e32 v147, 0xffff0000, v216
	v_fmamk_f32 v145, v145, 0x3fb504f3, v22
	v_fmamk_f32 v147, v147, 0x3fb504f3, v23
	v_cvt_pk_bf16_f32 v216, v145, v147
	v_lshlrev_b32_e32 v145, 16, v217
	v_and_b32_e32 v147, 0xffff0000, v217
	v_fmamk_f32 v145, v145, 0x3fb504f3, v24
	v_fmamk_f32 v147, v147, 0x3fb504f3, v25
	v_cvt_pk_bf16_f32 v217, v145, v147
	v_lshlrev_b32_e32 v145, 16, v218
	v_and_b32_e32 v147, 0xffff0000, v218
	v_fmamk_f32 v145, v145, 0x3fb504f3, v18
	v_fmamk_f32 v147, v147, 0x3fb504f3, v19
	v_cvt_pk_bf16_f32 v218, v145, v147
	v_lshlrev_b32_e32 v145, 16, v219
	v_and_b32_e32 v147, 0xffff0000, v219
	v_fmamk_f32 v145, v145, 0x3fb504f3, v20
	v_fmamk_f32 v147, v147, 0x3fb504f3, v21
	v_cvt_pk_bf16_f32 v219, v145, v147
	global_store_dwordx4 v[232:233], v[216:219], off offset:256
	v_lshlrev_b32_e32 v145, 16, v220
	v_and_b32_e32 v220, 0xffff0000, v220
	v_fmamk_f32 v145, v145, 0x3fb504f3, v14
	v_fmamk_f32 v220, v220, 0x3fb504f3, v15
	v_cvt_pk_bf16_f32 v220, v145, v220
	v_lshlrev_b32_e32 v145, 16, v221
	v_and_b32_e32 v221, 0xffff0000, v221
	v_fmamk_f32 v145, v145, 0x3fb504f3, v16
	v_fmamk_f32 v221, v221, 0x3fb504f3, v17
	v_cvt_pk_bf16_f32 v221, v145, v221
	v_lshlrev_b32_e32 v145, 16, v222
	v_and_b32_e32 v222, 0xffff0000, v222
	v_fmamk_f32 v145, v145, 0x3fb504f3, v10
	v_fmamk_f32 v222, v222, 0x3fb504f3, v11
	v_cvt_pk_bf16_f32 v222, v145, v222
	v_lshlrev_b32_e32 v145, 16, v223
	v_and_b32_e32 v223, 0xffff0000, v223
	v_fmamk_f32 v223, v223, 0x3fb504f3, v13
	v_fmamk_f32 v145, v145, 0x3fb504f3, v12
	v_cvt_pk_bf16_f32 v223, v145, v223
	global_store_dwordx4 v[234:235], v[220:223], off
	v_lshlrev_b32_e32 v145, 16, v224
	v_and_b32_e32 v224, 0xffff0000, v224
	v_fmamk_f32 v145, v145, 0x3fb504f3, v6
	v_fmamk_f32 v224, v224, 0x3fb504f3, v7
	v_cvt_pk_bf16_f32 v224, v145, v224
	v_lshlrev_b32_e32 v145, 16, v225
	v_and_b32_e32 v225, 0xffff0000, v225
	v_fmamk_f32 v145, v145, 0x3fb504f3, v8
	v_fmamk_f32 v225, v225, 0x3fb504f3, v9
	v_cvt_pk_bf16_f32 v225, v145, v225
	v_lshlrev_b32_e32 v145, 16, v226
	v_and_b32_e32 v226, 0xffff0000, v226
	v_fmamk_f32 v145, v145, 0x3fb504f3, v2
	v_fmamk_f32 v226, v226, 0x3fb504f3, v3
	v_cvt_pk_bf16_f32 v226, v145, v226
	v_lshlrev_b32_e32 v145, 16, v227
	v_and_b32_e32 v227, 0xffff0000, v227
	v_fmamk_f32 v227, v227, 0x3fb504f3, v5
	v_fmamk_f32 v145, v145, 0x3fb504f3, v4
	v_cvt_pk_bf16_f32 v227, v145, v227
	global_store_dwordx4 v[234:235], v[224:227], off offset:256

; __device__ __forceinline__ unsigned cvt_pk(float lo, float hi) { unsigned r; asm("v_cvt_pk_bf16_f32 %0, %1, %2" : "=v"(r) : "v"(lo), "v"(hi)); return r; }
; __device__ __forceinline__ float bflo(unsigned w) { return __uint_as_float(w << 16); }
; __device__ __forceinline__ float bfhi(unsigned w) { return __uint_as_float(w & 0xffff0000u); }
;     __device__ __forceinline__ void operator()(const f32x4 (&acc)[2][2][4][2], const Unit& u, int wr, int wc, int fr, int fq, LAS unsigned char*) const {
;     ...
; #pragma unroll
;         for (int ai = 0; ai < 2; ++ai)
; #pragma unroll
;             for (int m = 0; m < 4; ++m) { bf16_t* rowp = X + (size_t)(u.pm * 256 + ai * 128 + m * 16 + r0) * D + colt;
; #pragma unroll
;                 for (int bj = 0; bj < 2; ++bj) { const u32x4 xr = *(const u32x4*)(rowp + bj * 128); const f32x4 v0 = acc[ai][bj][m][0], v1 = acc[ai][bj][m][1];
;                     u32x4 w; w.x = cvt_pk(bflo(xr.x) * ALPHA + v0[0], bfhi(xr.x) * ALPHA + v0[1]); w.y = cvt_pk(bflo(xr.y) * ALPHA + v0[2], bfhi(xr.y) * ALPHA + v0[3]);
;                     w.z = cvt_pk(bflo(xr.z) * ALPHA + v1[0], bfhi(xr.z) * ALPHA + v1[1]); w.w = cvt_pk(bflo(xr.w) * ALPHA + v1[2], bfhi(xr.w) * ALPHA + v1[3]);
;                     if (!dry) *(u32x4*)(rowp + bj * 128) = w; } }
.LBB0_2046:
	v_lshl_or_b32 v178, s5, 8, v141
	s_mov_b64 s[60:61], -1
	s_cmp_gt_i32 s20, -1
	v_ashrrev_i32_e32 v179, 31, v178
	s_cbranch_scc1 .LBB0_2048
	s_lshl_b32 s4, s4, 8
	v_add_u32_e32 v130, s4, v140
	v_ashrrev_i32_e32 v131, 31, v130
	v_lshlrev_b64 v[130:131], 12, v[130:131]
	v_lshl_add_u64 v[228:229], s[24:25], 0, v[130:131]
	v_lshlrev_b64 v[130:131], 1, v[178:179]
	v_lshl_add_u64 v[228:229], v[228:229], 0, v[130:131]
	global_load_dwordx4 v[188:191], v[228:229], off
	s_mov_b64 s[60:61], 0
	global_load_dwordx4 v[192:195], v[228:229], off offset:256
	v_add_u32_e32 v230, s4, v142
	v_ashrrev_i32_e32 v231, 31, v230
	v_lshlrev_b64 v[230:231], 12, v[230:231]
	v_lshl_add_u64 v[230:231], s[24:25], 0, v[230:231]
	v_lshl_add_u64 v[230:231], v[230:231], 0, v[130:131]
	global_load_dwordx4 v[196:199], v[230:231], off
	global_load_dwordx4 v[200:203], v[230:231], off offset:256
	v_add_u32_e32 v232, s4, v144
	v_ashrrev_i32_e32 v233, 31, v232
	v_lshlrev_b64 v[232:233], 12, v[232:233]
	v_lshl_add_u64 v[232:233], s[24:25], 0, v[232:233]
	v_lshl_add_u64 v[232:233], v[232:233], 0, v[130:131]
	global_load_dwordx4 v[204:207], v[232:233], off
	global_load_dwordx4 v[216:219], v[232:233], off offset:256
	v_add_u32_e32 v234, s4, v146
	v_ashrrev_i32_e32 v235, 31, v234
	v_lshlrev_b64 v[234:235], 12, v[234:235]
	v_lshl_add_u64 v[234:235], s[24:25], 0, v[234:235]
	v_lshl_add_u64 v[234:235], v[234:235], 0, v[130:131]
	global_load_dwordx4 v[220:223], v[234:235], off
	global_load_dwordx4 v[224:227], v[234:235], off offset:256
	s_waitcnt vmcnt(0)
	v_lshlrev_b32_e32 v145, 16, v188
	v_and_b32_e32 v147, 0xffff0000, v188
	v_fmamk_f32 v145, v145, 0x3fb504f3, v126
	v_fmamk_f32 v147, v147, 0x3fb504f3, v127
	v_cvt_pk_bf16_f32 v188, v145, v147
	v_lshlrev_b32_e32 v145, 16, v189
	v_and_b32_e32 v147, 0xffff0000, v189
	v_fmamk_f32 v145, v145, 0x3fb504f3, v128
	v_fmamk_f32 v147, v147, 0x3fb504f3, v129
	v_cvt_pk_bf16_f32 v189, v145, v147
	v_lshlrev_b32_e32 v145, 16, v190
	v_and_b32_e32 v147, 0xffff0000, v190
	v_fmamk_f32 v145, v145, 0x3fb504f3, v122
	v_fmamk_f32 v147, v147, 0x3fb504f3, v123
	v_cvt_pk_bf16_f32 v190, v145, v147
	v_lshlrev_b32_e32 v145, 16, v191
	v_and_b32_e32 v147, 0xffff0000, v191
	v_fmamk_f32 v145, v145, 0x3fb504f3, v124
	v_fmamk_f32 v147, v147, 0x3fb504f3, v125
	v_cvt_pk_bf16_f32 v191, v145, v147
	global_store_dwordx4 v[228:229], v[188:191], off
	v_lshlrev_b32_e32 v145, 16, v192
	v_and_b32_e32 v147, 0xffff0000, v192
	v_fmamk_f32 v145, v145, 0x3fb504f3, v118
	v_fmamk_f32 v147, v147, 0x3fb504f3, v119
	v_cvt_pk_bf16_f32 v192, v145, v147
	v_lshlrev_b32_e32 v145, 16, v193
	v_and_b32_e32 v147, 0xffff0000, v193
	v_fmamk_f32 v145, v145, 0x3fb504f3, v120
	v_fmamk_f32 v147, v147, 0x3fb504f3, v121
	v_cvt_pk_bf16_f32 v193, v145, v147
	v_lshlrev_b32_e32 v145, 16, v194
	v_and_b32_e32 v147, 0xffff0000, v194
	v_fmamk_f32 v145, v145, 0x3fb504f3, v114
	v_fmamk_f32 v147, v147, 0x3fb504f3, v115
	v_cvt_pk_bf16_f32 v194, v145, v147
	v_lshlrev_b32_e32 v145, 16, v195
	v_and_b32_e32 v147, 0xffff0000, v195
	v_fmamk_f32 v145, v145, 0x3fb504f3, v116
	v_fmamk_f32 v147, v147, 0x3fb504f3, v117
	v_cvt_pk_bf16_f32 v195, v145, v147
	global_store_dwordx4 v[228:229], v[192:195], off offset:256
	v_lshlrev_b32_e32 v145, 16, v196
	v_and_b32_e32 v147, 0xffff0000, v196
	v_fmamk_f32 v145, v145, 0x3fb504f3, v110
	v_fmamk_f32 v147, v147, 0x3fb504f3, v111
	v_cvt_pk_bf16_f32 v196, v145, v147
	v_lshlrev_b32_e32 v145, 16, v197
	v_and_b32_e32 v147, 0xffff0000, v197
	v_fmamk_f32 v145, v145, 0x3fb504f3, v112
	v_fmamk_f32 v147, v147, 0x3fb504f3, v113
	v_cvt_pk_bf16_f32 v197, v145, v147
	v_lshlrev_b32_e32 v145, 16, v198
	v_and_b32_e32 v147, 0xffff0000, v198
	v_fmamk_f32 v145, v145, 0x3fb504f3, v106
	v_fmamk_f32 v147, v147, 0x3fb504f3, v107
	v_cvt_pk_bf16_f32 v198, v145, v147
	v_lshlrev_b32_e32 v145, 16, v199
	v_and_b32_e32 v147, 0xffff0000, v199
	v_fmamk_f32 v145, v145, 0x3fb504f3, v108
	v_fmamk_f32 v147, v147, 0x3fb504f3, v109
	v_cvt_pk_bf16_f32 v199, v145, v147
	global_store_dwordx4 v[230:231], v[196:199], off
	v_lshlrev_b32_e32 v145, 16, v200
	v_and_b32_e32 v147, 0xffff0000, v200
	v_fmamk_f32 v145, v145, 0x3fb504f3, v102
	v_fmamk_f32 v147, v147, 0x3fb504f3, v103
	v_cvt_pk_bf16_f32 v200, v145, v147
	v_lshlrev_b32_e32 v145, 16, v201
	v_and_b32_e32 v147, 0xffff0000, v201
	v_fmamk_f32 v145, v145, 0x3fb504f3, v104
	v_fmamk_f32 v147, v147, 0x3fb504f3, v105
	v_cvt_pk_bf16_f32 v201, v145, v147
	v_lshlrev_b32_e32 v145, 16, v202
	v_and_b32_e32 v147, 0xffff0000, v202
	v_fmamk_f32 v145, v145, 0x3fb504f3, v98
	v_fmamk_f32 v147, v147, 0x3fb504f3, v99
	v_cvt_pk_bf16_f32 v202, v145, v147
	v_lshlrev_b32_e32 v145, 16, v203
	v_and_b32_e32 v147, 0xffff0000, v203
	v_fmamk_f32 v145, v145, 0x3fb504f3, v100
	v_fmamk_f32 v147, v147, 0x3fb504f3, v101
	v_cvt_pk_bf16_f32 v203, v145, v147
	global_store_dwordx4 v[230:231], v[200:203], off offset:256
	v_lshlrev_b32_e32 v145, 16, v204
	v_and_b32_e32 v147, 0xffff0000, v204
	v_fmamk_f32 v145, v145, 0x3fb504f3, v94
	v_fmamk_f32 v147, v147, 0x3fb504f3, v95
	v_cvt_pk_bf16_f32 v204, v145, v147
	v_lshlrev_b32_e32 v145, 16, v205
	v_and_b32_e32 v147, 0xffff0000, v205
	v_fmamk_f32 v145, v145, 0x3fb504f3, v96
	v_fmamk_f32 v147, v147, 0x3fb504f3, v97
	v_cvt_pk_bf16_f32 v205, v145, v147
	v_lshlrev_b32_e32 v145, 16, v206
	v_and_b32_e32 v147, 0xffff0000, v206
	v_fmamk_f32 v145, v145, 0x3fb504f3, v90
	v_fmamk_f32 v147, v147, 0x3fb504f3, v91
	v_cvt_pk_bf16_f32 v206, v145, v147
	v_lshlrev_b32_e32 v145, 16, v207
	v_and_b32_e32 v147, 0xffff0000, v207
	v_fmamk_f32 v145, v145, 0x3fb504f3, v92
	v_fmamk_f32 v147, v147, 0x3fb504f3, v93
	v_cvt_pk_bf16_f32 v207, v145, v147
	global_store_dwordx4 v[232:233], v[204:207], off
; __device__ __forceinline__ unsigned cvt_pk(float lo, float hi) { unsigned r; asm("v_cvt_pk_bf16_f32 %0, %1, %2" : "=v"(r) : "v"(lo), "v"(hi)); return r; }
; __device__ __forceinline__ float bflo(unsigned w) { return __uint_as_float(w << 16); }
; __device__ __forceinline__ float bfhi(unsigned w) { return __uint_as_float(w & 0xffff0000u); }
;     __device__ __forceinline__ void operator()(const f32x4 (&acc)[2][2][4][2], const Unit& u, int wr, int wc, int fr, int fq, LAS unsigned char*) const {
;     ...
; #pragma unroll
;         for (int ai = 0; ai < 2; ++ai)
; #pragma unroll
;             for (int m = 0; m < 4; ++m) { bf16_t* rowp = X + (size_t)(u.pm * 256 + ai * 128 + m * 16 + r0) * D + colt;
; #pragma unroll
;                 for (int bj = 0; bj < 2; ++bj) { const u32x4 xr = *(const u32x4*)(rowp + bj * 128); const f32x4 v0 = acc[ai][bj][m][0], v1 = acc[ai][bj][m][1];
;                     u32x4 w; w.x = cvt_pk(bflo(xr.x) * ALPHA + v0[0], bfhi(xr.x) * ALPHA + v0[1]); w.y = cvt_pk(bflo(xr.y) * ALPHA + v0[2], bfhi(xr.y) * ALPHA + v0[3]);
;                     w.z = cvt_pk(bflo(xr.z) * ALPHA + v1[0], bfhi(xr.z) * ALPHA + v1[1]); w.w = cvt_pk(bflo(xr.w) * ALPHA + v1[2], bfhi(xr.w) * ALPHA + v1[3]);
;                     if (!dry) *(u32x4*)(rowp + bj * 128) = w; } }
	v_lshlrev_b32_e32 v145, 16, v216
	v_and_b32_e32 v147, 0xffff0000, v216
	v_fmamk_f32 v145, v145, 0x3fb504f3, v86
	v_fmamk_f32 v147, v147, 0x3fb504f3, v87
	v_cvt_pk_bf16_f32 v216, v145, v147
	v_lshlrev_b32_e32 v145, 16, v217
	v_and_b32_e32 v147, 0xffff0000, v217
	v_fmamk_f32 v145, v145, 0x3fb504f3, v88
	v_fmamk_f32 v147, v147, 0x3fb504f3, v89
	v_cvt_pk_bf16_f32 v217, v145, v147
	v_lshlrev_b32_e32 v145, 16, v218
	v_and_b32_e32 v147, 0xffff0000, v218
	v_fmamk_f32 v145, v145, 0x3fb504f3, v82
	v_fmamk_f32 v147, v147, 0x3fb504f3, v83
	v_cvt_pk_bf16_f32 v218, v145, v147
	v_lshlrev_b32_e32 v145, 16, v219
	v_and_b32_e32 v147, 0xffff0000, v219
	v_fmamk_f32 v145, v145, 0x3fb504f3, v84
	v_fmamk_f32 v147, v147, 0x3fb504f3, v85
	v_cvt_pk_bf16_f32 v219, v145, v147
	global_store_dwordx4 v[232:233], v[216:219], off offset:256
	v_lshlrev_b32_e32 v145, 16, v220
	v_and_b32_e32 v147, 0xffff0000, v220
	v_fmamk_f32 v145, v145, 0x3fb504f3, v78
	v_fmamk_f32 v147, v147, 0x3fb504f3, v79
	v_cvt_pk_bf16_f32 v220, v145, v147
	v_lshlrev_b32_e32 v145, 16, v221
	v_and_b32_e32 v147, 0xffff0000, v221
	v_fmamk_f32 v145, v145, 0x3fb504f3, v80
	v_fmamk_f32 v147, v147, 0x3fb504f3, v81
	v_cvt_pk_bf16_f32 v221, v145, v147
	v_lshlrev_b32_e32 v145, 16, v222
	v_and_b32_e32 v147, 0xffff0000, v222
	v_fmamk_f32 v145, v145, 0x3fb504f3, v74
	v_fmamk_f32 v147, v147, 0x3fb504f3, v75
	v_cvt_pk_bf16_f32 v222, v145, v147
	v_lshlrev_b32_e32 v145, 16, v223
	v_and_b32_e32 v147, 0xffff0000, v223
	v_fmamk_f32 v145, v145, 0x3fb504f3, v76
	v_fmamk_f32 v147, v147, 0x3fb504f3, v77
	v_cvt_pk_bf16_f32 v223, v145, v147
	global_store_dwordx4 v[234:235], v[220:223], off
	v_lshlrev_b32_e32 v145, 16, v224
	v_and_b32_e32 v147, 0xffff0000, v224
	v_fmamk_f32 v145, v145, 0x3fb504f3, v70
	v_fmamk_f32 v147, v147, 0x3fb504f3, v71
	v_cvt_pk_bf16_f32 v224, v145, v147
	v_lshlrev_b32_e32 v145, 16, v225
	v_and_b32_e32 v147, 0xffff0000, v225
	v_fmamk_f32 v145, v145, 0x3fb504f3, v72
	v_fmamk_f32 v147, v147, 0x3fb504f3, v73
	v_cvt_pk_bf16_f32 v225, v145, v147
	v_lshlrev_b32_e32 v145, 16, v226
	v_and_b32_e32 v147, 0xffff0000, v226
	v_fmamk_f32 v145, v145, 0x3fb504f3, v66
	v_fmamk_f32 v147, v147, 0x3fb504f3, v67
	v_cvt_pk_bf16_f32 v226, v145, v147
	v_lshlrev_b32_e32 v145, 16, v227
	v_and_b32_e32 v147, 0xffff0000, v227
	v_fmamk_f32 v145, v145, 0x3fb504f3, v68
	v_fmamk_f32 v147, v147, 0x3fb504f3, v69
	v_cvt_pk_bf16_f32 v227, v145, v147
	global_store_dwordx4 v[234:235], v[224:227], off offset:256
	v_add_u32_e32 v228, s4, v148
	v_ashrrev_i32_e32 v229, 31, v228
	v_lshlrev_b64 v[228:229], 12, v[228:229]
	v_lshl_add_u64 v[228:229], s[24:25], 0, v[228:229]
	v_lshl_add_u64 v[228:229], v[228:229], 0, v[130:131]
	global_load_dwordx4 v[188:191], v[228:229], off
	global_load_dwordx4 v[192:195], v[228:229], off offset:256
	v_add_u32_e32 v230, s4, v150
	v_ashrrev_i32_e32 v231, 31, v230
	v_lshlrev_b64 v[230:231], 12, v[230:231]
	v_lshl_add_u64 v[230:231], s[24:25], 0, v[230:231]
	v_lshl_add_u64 v[230:231], v[230:231], 0, v[130:131]
	global_load_dwordx4 v[196:199], v[230:231], off
	global_load_dwordx4 v[200:203], v[230:231], off offset:256
	v_add_u32_e32 v232, s4, v152
	v_ashrrev_i32_e32 v233, 31, v232
	v_lshlrev_b64 v[232:233], 12, v[232:233]
	v_lshl_add_u64 v[232:233], s[24:25], 0, v[232:233]
	v_lshl_add_u64 v[232:233], v[232:233], 0, v[130:131]
	global_load_dwordx4 v[204:207], v[232:233], off
	global_load_dwordx4 v[216:219], v[232:233], off offset:256
	v_add_u32_e32 v132, s4, v154
	v_ashrrev_i32_e32 v133, 31, v132
	v_lshlrev_b64 v[132:133], 12, v[132:133]
	v_lshl_add_u64 v[132:133], s[24:25], 0, v[132:133]
	v_lshl_add_u64 v[234:235], v[132:133], 0, v[130:131]
	global_load_dwordx4 v[220:223], v[234:235], off
	global_load_dwordx4 v[224:227], v[234:235], off offset:256
	s_waitcnt vmcnt(0)
; __device__ __forceinline__ unsigned cvt_pk(float lo, float hi) { unsigned r; asm("v_cvt_pk_bf16_f32 %0, %1, %2" : "=v"(r) : "v"(lo), "v"(hi)); return r; }
; __device__ __forceinline__ float bflo(unsigned w) { return __uint_as_float(w << 16); }
; __device__ __forceinline__ float bfhi(unsigned w) { return __uint_as_float(w & 0xffff0000u); }
;     __device__ __forceinline__ void operator()(const f32x4 (&acc)[2][2][4][2], const Unit& u, int wr, int wc, int fr, int fq, LAS unsigned char*) const {
;     ...
; #pragma unroll
;         for (int ai = 0; ai < 2; ++ai)
; #pragma unroll
;             for (int m = 0; m < 4; ++m) { bf16_t* rowp = X + (size_t)(u.pm * 256 + ai * 128 + m * 16 + r0) * D + colt;
; #pragma unroll
;                 for (int bj = 0; bj < 2; ++bj) { const u32x4 xr = *(const u32x4*)(rowp + bj * 128); const f32x4 v0 = acc[ai][bj][m][0], v1 = acc[ai][bj][m][1];
;                     u32x4 w; w.x = cvt_pk(bflo(xr.x) * ALPHA + v0[0], bfhi(xr.x) * ALPHA + v0[1]); w.y = cvt_pk(bflo(xr.y) * ALPHA + v0[2], bfhi(xr.y) * ALPHA + v0[3]);
;                     w.z = cvt_pk(bflo(xr.z) * ALPHA + v1[0], bfhi(xr.z) * ALPHA + v1[1]); w.w = cvt_pk(bflo(xr.w) * ALPHA + v1[2], bfhi(xr.w) * ALPHA + v1[3]);
;                     if (!dry) *(u32x4*)(rowp + bj * 128) = w; } }
	v_lshlrev_b32_e32 v145, 16, v188
	v_and_b32_e32 v147, 0xffff0000, v188
	v_fmamk_f32 v145, v145, 0x3fb504f3, v62
	v_fmamk_f32 v147, v147, 0x3fb504f3, v63
	v_cvt_pk_bf16_f32 v188, v145, v147
	v_lshlrev_b32_e32 v145, 16, v189
	v_and_b32_e32 v147, 0xffff0000, v189
	v_fmamk_f32 v145, v145, 0x3fb504f3, v64
	v_fmamk_f32 v147, v147, 0x3fb504f3, v65
	v_cvt_pk_bf16_f32 v189, v145, v147
	v_lshlrev_b32_e32 v145, 16, v190
	v_and_b32_e32 v147, 0xffff0000, v190
	v_fmamk_f32 v145, v145, 0x3fb504f3, v58
	v_fmamk_f32 v147, v147, 0x3fb504f3, v59
	v_cvt_pk_bf16_f32 v190, v145, v147
	v_lshlrev_b32_e32 v145, 16, v191
	v_and_b32_e32 v147, 0xffff0000, v191
	v_fmamk_f32 v145, v145, 0x3fb504f3, v60
	v_fmamk_f32 v147, v147, 0x3fb504f3, v61
	v_cvt_pk_bf16_f32 v191, v145, v147
	global_store_dwordx4 v[228:229], v[188:191], off
	v_lshlrev_b32_e32 v145, 16, v192
	v_and_b32_e32 v147, 0xffff0000, v192
	v_fmamk_f32 v145, v145, 0x3fb504f3, v54
	v_fmamk_f32 v147, v147, 0x3fb504f3, v55
	v_cvt_pk_bf16_f32 v192, v145, v147
	v_lshlrev_b32_e32 v145, 16, v193
	v_and_b32_e32 v147, 0xffff0000, v193
	v_fmamk_f32 v145, v145, 0x3fb504f3, v56
	v_fmamk_f32 v147, v147, 0x3fb504f3, v57
	v_cvt_pk_bf16_f32 v193, v145, v147
	v_lshlrev_b32_e32 v145, 16, v194
	v_and_b32_e32 v147, 0xffff0000, v194
	v_fmamk_f32 v145, v145, 0x3fb504f3, v50
	v_fmamk_f32 v147, v147, 0x3fb504f3, v51
	v_cvt_pk_bf16_f32 v194, v145, v147
	v_lshlrev_b32_e32 v145, 16, v195
	v_and_b32_e32 v147, 0xffff0000, v195
	v_fmamk_f32 v145, v145, 0x3fb504f3, v52
	v_fmamk_f32 v147, v147, 0x3fb504f3, v53
	v_cvt_pk_bf16_f32 v195, v145, v147
	global_store_dwordx4 v[228:229], v[192:195], off offset:256
	v_lshlrev_b32_e32 v145, 16, v196
	v_and_b32_e32 v147, 0xffff0000, v196
	v_fmamk_f32 v145, v145, 0x3fb504f3, v46
	v_fmamk_f32 v147, v147, 0x3fb504f3, v47
	v_cvt_pk_bf16_f32 v196, v145, v147
	v_lshlrev_b32_e32 v145, 16, v197
	v_and_b32_e32 v147, 0xffff0000, v197
	v_fmamk_f32 v145, v145, 0x3fb504f3, v48
	v_fmamk_f32 v147, v147, 0x3fb504f3, v49
	v_cvt_pk_bf16_f32 v197, v145, v147
	v_lshlrev_b32_e32 v145, 16, v198
	v_and_b32_e32 v147, 0xffff0000, v198
	v_fmamk_f32 v145, v145, 0x3fb504f3, v42
	v_fmamk_f32 v147, v147, 0x3fb504f3, v43
	v_cvt_pk_bf16_f32 v198, v145, v147
	v_lshlrev_b32_e32 v145, 16, v199
	v_and_b32_e32 v147, 0xffff0000, v199
	v_fmamk_f32 v145, v145, 0x3fb504f3, v44
	v_fmamk_f32 v147, v147, 0x3fb504f3, v45
	v_cvt_pk_bf16_f32 v199, v145, v147
	global_store_dwordx4 v[230:231], v[196:199], off
	v_lshlrev_b32_e32 v145, 16, v200
	v_and_b32_e32 v147, 0xffff0000, v200
	v_fmamk_f32 v145, v145, 0x3fb504f3, v38
	v_fmamk_f32 v147, v147, 0x3fb504f3, v39
	v_cvt_pk_bf16_f32 v200, v145, v147
	v_lshlrev_b32_e32 v145, 16, v201
	v_and_b32_e32 v147, 0xffff0000, v201
	v_fmamk_f32 v145, v145, 0x3fb504f3, v40
	v_fmamk_f32 v147, v147, 0x3fb504f3, v41
	v_cvt_pk_bf16_f32 v201, v145, v147
	v_lshlrev_b32_e32 v145, 16, v202
	v_and_b32_e32 v147, 0xffff0000, v202
	v_fmamk_f32 v145, v145, 0x3fb504f3, v34
	v_fmamk_f32 v147, v147, 0x3fb504f3, v35
	v_cvt_pk_bf16_f32 v202, v145, v147
	v_lshlrev_b32_e32 v145, 16, v203
	v_and_b32_e32 v147, 0xffff0000, v203
	v_fmamk_f32 v145, v145, 0x3fb504f3, v36
	v_fmamk_f32 v147, v147, 0x3fb504f3, v37
	v_cvt_pk_bf16_f32 v203, v145, v147
	global_store_dwordx4 v[230:231], v[200:203], off offset:256
	v_lshlrev_b32_e32 v145, 16, v204
	v_and_b32_e32 v147, 0xffff0000, v204
	v_fmamk_f32 v145, v145, 0x3fb504f3, v30
	v_fmamk_f32 v147, v147, 0x3fb504f3, v31
	v_cvt_pk_bf16_f32 v204, v145, v147
	v_lshlrev_b32_e32 v145, 16, v205
	v_and_b32_e32 v147, 0xffff0000, v205
	v_fmamk_f32 v145, v145, 0x3fb504f3, v32
	v_fmamk_f32 v147, v147, 0x3fb504f3, v33
	v_cvt_pk_bf16_f32 v205, v145, v147
	v_lshlrev_b32_e32 v145, 16, v206
	v_and_b32_e32 v147, 0xffff0000, v206
	v_fmamk_f32 v145, v145, 0x3fb504f3, v26
	v_fmamk_f32 v147, v147, 0x3fb504f3, v27
	v_cvt_pk_bf16_f32 v206, v145, v147
	v_lshlrev_b32_e32 v145, 16, v207
	v_and_b32_e32 v147, 0xffff0000, v207
	v_fmamk_f32 v145, v145, 0x3fb504f3, v28
	v_fmamk_f32 v147, v147, 0x3fb504f3, v29
	v_cvt_pk_bf16_f32 v207, v145, v147
	global_store_dwordx4 v[232:233], v[204:207], off
	v_lshlrev_b32_e32 v145, 16, v216
	v_and_b32_e32 v147, 0xffff0000, v216
	v_fmamk_f32 v145, v145, 0x3fb504f3, v22
	v_fmamk_f32 v147, v147, 0x3fb504f3, v23
	v_cvt_pk_bf16_f32 v216, v145, v147
	v_lshlrev_b32_e32 v145, 16, v217
	v_and_b32_e32 v147, 0xffff0000, v217
	v_fmamk_f32 v145, v145, 0x3fb504f3, v24
	v_fmamk_f32 v147, v147, 0x3fb504f3, v25
	v_cvt_pk_bf16_f32 v217, v145, v147
	v_lshlrev_b32_e32 v145, 16, v218
	v_and_b32_e32 v147, 0xffff0000, v218
	v_fmamk_f32 v145, v145, 0x3fb504f3, v18
	v_fmamk_f32 v147, v147, 0x3fb504f3, v19
	v_cvt_pk_bf16_f32 v218, v145, v147
	v_lshlrev_b32_e32 v145, 16, v219
	v_and_b32_e32 v147, 0xffff0000, v219
	v_fmamk_f32 v145, v145, 0x3fb504f3, v20
	v_fmamk_f32 v147, v147, 0x3fb504f3, v21
	v_cvt_pk_bf16_f32 v219, v145, v147
	global_store_dwordx4 v[232:233], v[216:219], off offset:256
	v_lshlrev_b32_e32 v145, 16, v220
	v_and_b32_e32 v220, 0xffff0000, v220
	v_fmamk_f32 v145, v145, 0x3fb504f3, v14
	v_fmamk_f32 v220, v220, 0x3fb504f3, v15
	v_cvt_pk_bf16_f32 v220, v145, v220
	v_lshlrev_b32_e32 v145, 16, v221
	v_and_b32_e32 v221, 0xffff0000, v221
	v_fmamk_f32 v145, v145, 0x3fb504f3, v16
	v_fmamk_f32 v221, v221, 0x3fb504f3, v17
	v_cvt_pk_bf16_f32 v221, v145, v221
	v_lshlrev_b32_e32 v145, 16, v222
	v_and_b32_e32 v222, 0xffff0000, v222
	v_fmamk_f32 v145, v145, 0x3fb504f3, v10
	v_fmamk_f32 v222, v222, 0x3fb504f3, v11
	v_cvt_pk_bf16_f32 v222, v145, v222
	v_lshlrev_b32_e32 v145, 16, v223
	v_and_b32_e32 v223, 0xffff0000, v223
	v_fmamk_f32 v223, v223, 0x3fb504f3, v13
	v_fmamk_f32 v145, v145, 0x3fb504f3, v12
	v_cvt_pk_bf16_f32 v223, v145, v223
	global_store_dwordx4 v[234:235], v[220:223], off
	v_lshlrev_b32_e32 v145, 16, v224
	v_and_b32_e32 v224, 0xffff0000, v224
	v_fmamk_f32 v145, v145, 0x3fb504f3, v6
	v_fmamk_f32 v224, v224, 0x3fb504f3, v7
	v_cvt_pk_bf16_f32 v224, v145, v224
	v_lshlrev_b32_e32 v145, 16, v225
	v_and_b32_e32 v225, 0xffff0000, v225
	v_fmamk_f32 v145, v145, 0x3fb504f3, v8
	v_fmamk_f32 v225, v225, 0x3fb504f3, v9
	v_cvt_pk_bf16_f32 v225, v145, v225
	v_lshlrev_b32_e32 v145, 16, v226
	v_and_b32_e32 v226, 0xffff0000, v226
	v_fmamk_f32 v145, v145, 0x3fb504f3, v2
	v_fmamk_f32 v226, v226, 0x3fb504f3, v3
	v_cvt_pk_bf16_f32 v226, v145, v226
	v_lshlrev_b32_e32 v145, 16, v227
	v_and_b32_e32 v227, 0xffff0000, v227
	v_fmamk_f32 v227, v227, 0x3fb504f3, v5
	v_fmamk_f32 v145, v145, 0x3fb504f3, v4
	v_cvt_pk_bf16_f32 v227, v145, v227
	global_store_dwordx4 v[234:235], v[224:227], off offset:256
